# diff attention: waves whose 32 queries are all padding positions (qb=16, qsub>=1; never stored) skip their key tiles and always vote for the exact early exit (on v68)
# baseline (speedup 1.0000x reference)
.LBB0_298:
	s_or_b64 exec, exec, s[4:5]
	v_mov_b32_e32 v1, s33
	s_waitcnt lgkmcnt(0)
	s_barrier
	ds_read_b32 v1, v1
	s_movk_i32 s4, 0x43f
	s_waitcnt lgkmcnt(0)
	v_cmp_lt_i32_e32 vcc, s4, v1
	v_readfirstlane_b32 s6, v1
	s_mov_b64 s[4:5], -1
	s_cbranch_vccnz .LBB0_293
	s_and_b32 s16, s6, 15
	s_bfe_u32 s4, s6, 0x20004
	s_lshl_b32 s7, s16, 4
	v_readlane_b32 s8, v254, 43
	s_lshl_b32 s6, s6, 1
	s_or_b32 s7, s7, s8
	s_and_b32 s8, s6, 0xffffff80
	v_mov_b32_e32 v187, v202
	s_sub_i32 s37, 0x800, s8
	s_add_i32 s54, s37, s63
	v_and_b32_e32 v186, 31, v187
	v_or_b32_e32 v2, s54, v186
	s_mulk_i32 s4, 0x810
	s_mov_b32 s5, s89
	v_ashrrev_i32_e32 v3, 31, v2
	v_lshl_add_u64 v[6:7], v[2:3], 0, s[4:5]
	v_mov_b32_e32 v1, s7
	v_lshlrev_b64 v[6:7], 13, v[6:7]
	v_readlane_b32 s6, v254, 48
	v_ashrrev_i32_e32 v201, 5, v187
	v_lshl_add_u64 v[6:7], s[10:11], 0, v[6:7]
	s_lshl_b32 s88, s16, 8
	v_readlane_b32 s7, v254, 49
	v_lshl_add_u64 v[6:7], v[6:7], 0, s[88:89]
	s_mov_b32 s7, s89
	v_lshlrev_b32_e32 v188, 3, v201
	v_lshl_add_u64 v[6:7], v[6:7], 0, s[6:7]
	v_ashrrev_i32_e32 v189, 31, v188
	v_lshl_add_u64 v[6:7], v[188:189], 1, v[6:7]
	global_load_dwordx2 v[4:5], v1, s[76:77] offset:2048
	global_load_dwordx4 v[116:119], v[6:7], off
	global_load_dwordx4 v[120:123], v[6:7], off offset:32
	global_load_dwordx4 v[124:127], v[6:7], off offset:64
	global_load_dwordx4 v[128:131], v[6:7], off offset:96
	s_mov_b32 s38, s6
	v_writelane_b32 v254, s38, 48
	s_lshl_b32 s9, s16, 7
	s_waitcnt vmcnt(3)
	v_and_b32_e32 v1, 0xffff0000, v116
	v_lshlrev_b32_e32 v3, 16, v116
	v_mul_f32_e32 v1, v1, v1
	v_fmac_f32_e32 v1, v3, v3
	v_lshlrev_b32_e32 v3, 16, v117
	v_fmac_f32_e32 v1, v3, v3
	v_and_b32_e32 v3, 0xffff0000, v117
	v_fmac_f32_e32 v1, v3, v3
	v_lshlrev_b32_e32 v3, 16, v118
	v_fmac_f32_e32 v1, v3, v3
	v_and_b32_e32 v3, 0xffff0000, v118
	v_fmac_f32_e32 v1, v3, v3
	v_lshlrev_b32_e32 v3, 16, v119
	v_fmac_f32_e32 v1, v3, v3
	v_and_b32_e32 v3, 0xffff0000, v119
	v_fmac_f32_e32 v1, v3, v3
	s_waitcnt vmcnt(2)
	v_lshlrev_b32_e32 v3, 16, v120
	v_fmac_f32_e32 v1, v3, v3
	v_and_b32_e32 v3, 0xffff0000, v120
	v_fmac_f32_e32 v1, v3, v3
	v_lshlrev_b32_e32 v3, 16, v121
	v_fmac_f32_e32 v1, v3, v3
	v_and_b32_e32 v3, 0xffff0000, v121
	v_fmac_f32_e32 v1, v3, v3
	v_lshlrev_b32_e32 v3, 16, v122
	v_fmac_f32_e32 v1, v3, v3
	v_and_b32_e32 v3, 0xffff0000, v122
	v_fmac_f32_e32 v1, v3, v3
	v_lshlrev_b32_e32 v3, 16, v123
	v_fmac_f32_e32 v1, v3, v3
	v_and_b32_e32 v3, 0xffff0000, v123
	v_fmac_f32_e32 v1, v3, v3
	s_waitcnt vmcnt(1)
	v_lshlrev_b32_e32 v3, 16, v124
	v_fmac_f32_e32 v1, v3, v3
	v_and_b32_e32 v3, 0xffff0000, v124
	v_fmac_f32_e32 v1, v3, v3
	v_lshlrev_b32_e32 v3, 16, v125
	v_fmac_f32_e32 v1, v3, v3
	v_and_b32_e32 v3, 0xffff0000, v125
	v_fmac_f32_e32 v1, v3, v3
	v_lshlrev_b32_e32 v3, 16, v126
	v_fmac_f32_e32 v1, v3, v3
	v_and_b32_e32 v3, 0xffff0000, v126
	v_fmac_f32_e32 v1, v3, v3
	v_lshlrev_b32_e32 v3, 16, v127
	v_fmac_f32_e32 v1, v3, v3
	v_and_b32_e32 v3, 0xffff0000, v127
	v_fmac_f32_e32 v1, v3, v3
	s_waitcnt vmcnt(0)
	v_lshlrev_b32_e32 v3, 16, v128
	v_fmac_f32_e32 v1, v3, v3
	v_and_b32_e32 v3, 0xffff0000, v128
	v_fmac_f32_e32 v1, v3, v3
	v_lshlrev_b32_e32 v3, 16, v129
	v_fmac_f32_e32 v1, v3, v3
	v_and_b32_e32 v3, 0xffff0000, v129
	v_fmac_f32_e32 v1, v3, v3
	v_lshlrev_b32_e32 v3, 16, v130
	v_fmac_f32_e32 v1, v3, v3
	v_and_b32_e32 v3, 0xffff0000, v130
	v_fmac_f32_e32 v1, v3, v3
	v_lshlrev_b32_e32 v3, 16, v131
	v_fmac_f32_e32 v1, v3, v3
	v_and_b32_e32 v3, 0xffff0000, v131
	v_fmac_f32_e32 v1, v3, v3
	ds_bpermute_b32 v3, v200, v1
	v_writelane_b32 v254, s39, 49
	s_mov_b64 s[6:7], exec
	v_readlane_b32 s38, v254, 51
	v_readlane_b32 s39, v254, 52
	s_and_b64 s[38:39], s[6:7], s[38:39]
	s_mov_b64 exec, s[38:39]
	ds_write_b32 v203, v0
	s_or_b64 exec, exec, s[6:7]
	s_add_i32 s5, s54, -16
	s_lshr_b32 s6, s54, 6
	s_add_i32 s42, s16, 1
	s_lshr_b32 s5, s5, 6
	s_add_i32 s6, s6, 1
	s_cmp_gt_i32 s54, -1
	s_cselect_b32 s6, s6, 0
	s_lshl_b32 s7, s6, 6
	s_lshl_b32 s6, s6, 1
	s_cmpk_lt_u32 s7, 0x880
	s_cselect_b32 s55, s6, 0x43
	s_cmpk_gt_i32 s54, 0x81f
	s_cselect_b32 s55, 0, s55
	s_mov_b32 s98, 0xf149f2ca
	s_cselect_b32 s98, 0x7149f2ca, s98
	s_sub_i32 s6, 0x900, s8
	s_lshr_b32 s6, s6, 7
	s_add_i32 s38, s6, -1
	v_lshrrev_b32_e32 v6, 3, v164
	v_or_b32_e32 v8, s9, v165
	s_lshl_b32 s88, s4, 1
	v_add_lshl_u32 v6, s4, v6, 13
	v_mov_b32_e32 v7, v0
	v_mul_u32_u24_e32 v8, 0x2200, v8
	s_cmp_gt_i32 s54, 15
	v_lshl_add_u64 v[6:7], s[10:11], 0, v[6:7]
	v_lshlrev_b32_e32 v8, 1, v8
	v_mov_b32_e32 v9, v0
	s_cselect_b64 s[16:17], -1, 0
	s_lshl_b32 s6, s9, 1
	s_mov_b32 s7, s89
	v_lshl_add_u64 v[8:9], s[86:87], 0, v[8:9]
	s_cmpk_lt_u32 s37, 0x800
	v_lshl_add_u64 v[6:7], v[6:7], 0, s[6:7]
	v_mov_b32_e32 v169, v0
	v_lshl_add_u64 v[8:9], v[8:9], 0, s[88:89]
	s_cselect_b32 s88, s38, 16
	v_lshl_add_u64 v[6:7], v[6:7], 0, v[168:169]
	s_mov_b64 s[38:39], 0x1000
	v_mov_b32_e32 v167, v0
	v_lshl_add_u64 v[192:193], v[6:7], 0, s[38:39]
	s_lshl_b64 s[38:39], s[88:89], 20
	v_lshl_add_u64 v[190:191], v[8:9], 0, v[166:167]
	v_lshl_add_u64 v[6:7], v[192:193], 0, s[38:39]
	s_mov_b64 s[40:41], 0x88000
	v_add_co_u32_e32 v8, vcc, s24, v6
	s_lshl_b64 s[38:39], s[88:89], 8
	v_lshl_add_u64 v[194:195], v[190:191], 0, s[40:41]
	s_mov_b64 s[40:41], 0x110000
	v_addc_co_u32_e32 v9, vcc, 0, v7, vcc
	global_load_dwordx4 v[132:135], v[6:7], off
	global_load_dwordx4 v[136:139], v[6:7], off offset:128
	global_load_dwordx4 v[140:143], v[8:9], off
	global_load_dwordx4 v[144:147], v[8:9], off offset:128
	v_lshl_add_u64 v[6:7], v[190:191], 0, s[38:39]
	v_lshl_add_u64 v[196:197], v[190:191], 0, s[40:41]
	s_mov_b64 s[40:41], 0x198000
	v_lshl_add_u64 v[8:9], v[194:195], 0, s[38:39]
	global_load_dwordx4 v[148:151], v[6:7], off
	global_load_dwordx4 v[152:155], v[8:9], off
	v_lshl_add_u64 v[6:7], v[196:197], 0, s[38:39]
	v_lshl_add_u64 v[198:199], v[190:191], 0, s[40:41]
	v_lshl_add_u64 v[8:9], v[198:199], 0, s[38:39]
	global_load_dwordx4 v[156:159], v[6:7], off
	global_load_dwordx4 v[160:163], v[8:9], off
	v_add_f32_e32 v4, v4, v5
	s_waitcnt lgkmcnt(0)
	v_add_f32_e32 v1, v1, v3
	v_mul_f32_e32 v1, v4, v1
	s_mov_b32 s9, 0xf800000
	v_add_u32_e32 v5, -16, v2
	v_mul_f32_e32 v3, 0x4f800000, v1
	v_cmp_gt_f32_e32 vcc, s9, v1
	v_lshrrev_b32_e32 v167, 6, v5
	v_cvt_f32_ubyte0_e32 v5, s42
	v_cndmask_b32_e32 v1, v1, v3, vcc
	v_mul_f32_e32 v5, -0.5, v5
	v_sqrt_f32_e32 v3, v1
	v_exp_f32_e32 v5, v5
	s_lshl_b32 s57, s88, 16
	s_and_b32 s9, s57, 0x10000
	v_add_u32_e32 v4, -1, v3
	v_mul_f32_e32 v214, 0xbfb8aa3b, v5
	v_fma_f32 v5, -v4, v3, v1
	v_cmp_ge_f32_e64 s[40:41], 0, v5
	v_add_u32_e32 v5, 1, v3
	v_lshlrev_b32_e32 v6, 1, v186
	v_cndmask_b32_e64 v4, v3, v4, s[40:41]
	v_fma_f32 v3, -v5, v3, v1
	v_cmp_lt_f32_e64 s[40:41], 0, v3
	v_lshrrev_b32_e32 v7, 1, v187
	v_and_b32_e32 v6, 8, v6
	v_cndmask_b32_e64 v3, v4, v5, s[40:41]
	v_mul_f32_e32 v4, 0x37800000, v3
	v_cndmask_b32_e32 v3, v3, v4, vcc
	v_mov_b32_e32 v4, 0x260
	v_cmp_class_f32_e32 vcc, v1, v4
	v_and_b32_e32 v7, 4, v7
	v_and_b32_e32 v8, 19, v187
	v_cndmask_b32_e32 v1, v3, v1, vcc
	v_mul_f32_e32 v1, 0x3e38aa3b, v1
	v_fmamk_f32 v215, v1, 0x3f8020c5, v208
	v_add_u32_e32 v1, s9, v204
	v_or3_b32 v6, v7, v8, v6
	v_lshrrev_b32_e32 v7, 1, v6
	v_cmp_gt_i32_e64 s[38:39], 16, v2
	s_waitcnt vmcnt(7)
	ds_write_b128 v1, v[132:135]
	s_waitcnt vmcnt(5)
	ds_write_b128 v1, v[140:143] offset:8192
	ds_write_b128 v1, v[136:139] offset:16384
	s_waitcnt vmcnt(4)
	ds_write_b128 v1, v[144:147] offset:24576
	s_waitcnt vmcnt(3)
	ds_write_b128 v1, v[148:151] offset:32768
	s_waitcnt vmcnt(2)
	ds_write_b128 v1, v[152:155] offset:40960
	s_waitcnt vmcnt(1)
	ds_write_b128 v1, v[156:159] offset:49152
	s_waitcnt vmcnt(0)
	ds_write_b128 v1, v[160:163] offset:57344
	v_cvt_f32_i32_e32 v1, v2
	v_bitop3_b32 v2, v7, v201, 7 bitop3:0x6c
	v_lshlrev_b32_e32 v232, 4, v2
	v_readlane_b32 s42, v254, 45
	v_mul_f32_e64 v231, -v214, v1
	v_add_u32_e32 v1, 2, v201
	v_bitop3_b32 v2, v7, v1, 7 bitop3:0x6c
	v_lshlrev_b32_e32 v233, 4, v2
	v_add_u32_e32 v2, 4, v201
	v_bitop3_b32 v3, v7, v2, 7 bitop3:0x6c
	v_lshlrev_b32_e32 v234, 4, v3
	v_add_u32_e32 v3, 6, v201
	v_bitop3_b32 v4, v7, v3, 7 bitop3:0x6c
	v_lshlrev_b32_e32 v235, 4, v4
	v_add_u32_e32 v4, 12, v201
	v_bitop3_b32 v4, v4, v187, 15 bitop3:0x78
	v_lshlrev_b32_e32 v236, 4, v4
	v_add_u32_e32 v4, 14, v201
	v_bitop3_b32 v4, v4, v187, 15 bitop3:0x78
	v_lshlrev_b32_e32 v237, 4, v4
	v_add_u32_e32 v4, 8, v201
	v_bitop3_b32 v1, v1, v187, 15 bitop3:0x78
	v_bitop3_b32 v4, v4, v187, 15 bitop3:0x78
	v_bitop3_b32 v2, v2, v187, 15 bitop3:0x78
	v_lshlrev_b32_e32 v243, 4, v1
	v_add_u32_e32 v1, s42, v186
	v_lshlrev_b32_e32 v238, 4, v4
	v_add_u32_e32 v4, 10, v201
	v_lshlrev_b32_e32 v240, 4, v2
	v_bitop3_b32 v2, v3, v187, 15 bitop3:0x78
	s_lshl_b32 s58, s88, 7
	v_sub_u32_e32 v1, v1, v188
	v_bitop3_b32 v4, v4, v187, 15 bitop3:0x78
	v_lshlrev_b32_e32 v241, 4, v2
	v_bitop3_b32 v2, v201, v187, 15 bitop3:0x78
	v_subrev_u32_e32 v1, s58, v1
	v_mov_b32_e32 v14, v0
	v_mov_b32_e32 v15, v0
	v_lshlrev_b32_e32 v213, 7, v6
	v_lshlrev_b32_e32 v239, 4, v4
	v_lshlrev_b32_e32 v242, 4, v2
	s_add_i32 s9, s88, -1
	v_subrev_u32_e32 v244, s8, v1
	v_mov_b32_e32 v1, v0
	v_mov_b32_e32 v2, v0
	v_mov_b32_e32 v3, v0
	v_mov_b32_e32 v4, v0
	v_mov_b32_e32 v5, v0
	v_mov_b32_e32 v6, v0
	v_mov_b32_e32 v7, v0
	v_mov_b32_e32 v8, v0
	v_mov_b32_e32 v9, v0
	v_mov_b32_e32 v10, v0
	v_mov_b32_e32 v11, v0
	v_mov_b32_e32 v12, v0
	v_mov_b32_e32 v13, v0
	v_mov_b64_e32 v[30:31], v[14:15]
	v_mov_b64_e32 v[46:47], v[14:15]
	v_mov_b64_e32 v[62:63], v[14:15]
	v_mov_b64_e32 v[78:79], v[14:15]
	s_mov_b32 s56, 1
	s_mov_b32 s7, 0
	v_lshlrev_b32_e32 v169, 8, v186
	v_mul_f32_e32 v216, 0x80000000, v214
	v_mul_f32_e32 v217, -2.0, v214
	v_mul_f32_e32 v218, 0xc0400000, v214
	v_mul_f32_e32 v219, -4.0, v214
	v_mul_f32_e32 v220, 0xc0a00000, v214
	v_mul_f32_e32 v221, 0xc0c00000, v214
	v_mul_f32_e32 v222, 0xc0e00000, v214
	v_mul_f32_e32 v223, 0xc1800000, v214
	v_mul_f32_e32 v224, 0xc1880000, v214
	v_mul_f32_e32 v225, 0xc1900000, v214
	v_mul_f32_e32 v226, 0xc1980000, v214
	v_mul_f32_e32 v227, 0xc1a00000, v214
	v_mul_f32_e32 v228, 0xc1a80000, v214
	v_mul_f32_e32 v229, 0xc1b00000, v214
	v_mul_f32_e32 v230, 0xc1b80000, v214
	v_cmp_eq_u32_e64 s[40:41], 0, v187
	s_lshl_b32 s59, s88, 2
	v_mov_b32_e32 v245, 0
	v_mov_b32_e32 v246, s98
	v_readlane_b32 s60, v254, 50
	v_readlane_b32 s61, v254, 38
	s_mov_b32 s88, s9
	v_mov_b64_e32 v[28:29], v[12:13]
	v_mov_b64_e32 v[26:27], v[10:11]
	v_mov_b64_e32 v[24:25], v[8:9]
	v_mov_b64_e32 v[22:23], v[6:7]
	v_mov_b64_e32 v[20:21], v[4:5]
	v_mov_b64_e32 v[18:19], v[2:3]
	v_mov_b64_e32 v[16:17], v[0:1]
	v_mov_b64_e32 v[44:45], v[12:13]
	v_mov_b64_e32 v[42:43], v[10:11]
	v_mov_b64_e32 v[40:41], v[8:9]
	v_mov_b64_e32 v[38:39], v[6:7]
	v_mov_b64_e32 v[36:37], v[4:5]
	v_mov_b64_e32 v[34:35], v[2:3]
	v_mov_b64_e32 v[32:33], v[0:1]
	v_mov_b64_e32 v[60:61], v[12:13]
	v_mov_b64_e32 v[58:59], v[10:11]
	v_mov_b64_e32 v[56:57], v[8:9]
	v_mov_b64_e32 v[54:55], v[6:7]
	v_mov_b64_e32 v[52:53], v[4:5]
	v_mov_b64_e32 v[50:51], v[2:3]
	v_mov_b64_e32 v[48:49], v[0:1]
	v_mov_b64_e32 v[76:77], v[12:13]
	v_mov_b64_e32 v[74:75], v[10:11]
	v_mov_b64_e32 v[72:73], v[8:9]
	v_mov_b64_e32 v[70:71], v[6:7]
	v_mov_b64_e32 v[68:69], v[4:5]
	v_mov_b64_e32 v[66:67], v[2:3]
	v_mov_b64_e32 v[64:65], v[0:1]
	s_waitcnt vmcnt(0) expcnt(0) lgkmcnt(0)
	s_barrier
	s_branch .LBB0_303
